# cache-policy hint: merge-epilogue PROJ LDS-DMA loads marked nt (streamed once) so they do not displace GEMM operands in L2
# baseline (speedup 1.0000x reference)
.Lw2_nowait:
	v_lshl_add_u32 v250, s52, 8, v146
	v_lshl_or_b32 v251, s26, 6, v148
	v_lshlrev_b32_e32 v251, 1, v251
	v_mbcnt_lo_u32_b32 v140, -1, 0
	v_mbcnt_hi_u32_b32 v140, -1, v140
	v_lshrrev_b32_e32 v141, 3, v140
	s_lshl_b32 s27, s3, 3
	v_add_u32_e32 v141, s27, v141
	v_and_b32_e32 v142, 7, v140
	v_bfe_u32 v143, v141, 1, 3
	v_xor_b32_e32 v142, v142, v143
	v_and_b32_e32 v143, 31, v141
	v_lshrrev_b32_e32 v141, 5, v141
	v_lshrrev_b32_e32 v144, 4, v143
	v_and_b32_e32 v143, 15, v143
	v_lshl_or_b32 v143, v144, 6, v143
	s_lshl_b32 s27, s52, 8
	v_add_u32_e32 v143, s27, v143
	v_lshlrev_b32_e32 v143, 13, v143
	v_lshl_add_u32 v143, v141, 11, v143
	v_lshl_add_u32 v143, v142, 4, v143
	s_lshl_b32 s27, s26, 7
	v_add_u32_e32 v143, s27, v143
	s_lshl_b32 s27, s3, 10
	s_add_i32 s27, s27, 0x20000
	v_add_u32_e32 v253, 0x0, v143
	s_add_i32 m0, s27, 0x0
	s_nop 0
	global_load_lds_dwordx4 v253, s[6:7] nt
	v_add_u32_e32 v253, 0x1000, v143
	s_add_i32 m0, s27, 0x2000
	s_nop 0
	global_load_lds_dwordx4 v253, s[6:7] nt
	v_lshrrev_b32_e32 v144, 6, v146
	v_and_b32_e32 v145, 15, v146
	v_lshl_or_b32 v144, v144, 4, v145
	v_bfe_u32 v145, v144, 1, 3
	v_lshrrev_b32_e32 v252, 4, v148
	v_bfe_u32 v254, v148, 3, 1
	v_lshl_or_b32 v252, v252, 1, v254
	v_xor_b32_e32 v252, v252, v145
	v_lshlrev_b32_e32 v252, 4, v252
	v_bfe_u32 v254, v148, 2, 1
	v_lshl_or_b32 v252, v254, 3, v252
	v_lshl_add_u32 v252, v144, 7, v252
	v_add_u32_e32 v252, 0x20000, v252
	v_mov_b32_e32 v224, 0xbfb8aa3b
	v_mov_b32_e32 v225, 0xbfb8aa3b
	v_mov_b32_e32 v226, 1.0
	v_mov_b32_e32 v227, 1.0
	v_mov_b32_e32 v228, 0
	v_mov_b32_e32 v229, 0
	v_pk_mul_f32 v[150:151], v[126:127], v[224:225]
	v_pk_mul_f32 v[152:153], v[128:129], v[224:225]
	v_pk_mul_f32 v[154:155], v[122:123], v[224:225]
	v_pk_mul_f32 v[156:157], v[124:125], v[224:225]
	v_pk_mul_f32 v[158:159], v[118:119], v[224:225]
	v_pk_mul_f32 v[160:161], v[120:121], v[224:225]
	v_pk_mul_f32 v[162:163], v[114:115], v[224:225]
	v_pk_mul_f32 v[164:165], v[116:117], v[224:225]
	v_exp_f32_e32 v150, v150
	v_exp_f32_e32 v151, v151
	v_exp_f32_e32 v152, v152
	v_exp_f32_e32 v153, v153
	v_exp_f32_e32 v154, v154
	v_exp_f32_e32 v155, v155
	v_exp_f32_e32 v156, v156
	v_exp_f32_e32 v157, v157
	v_exp_f32_e32 v158, v158
	v_exp_f32_e32 v159, v159
	v_exp_f32_e32 v160, v160
	v_exp_f32_e32 v161, v161
	v_exp_f32_e32 v162, v162
	v_exp_f32_e32 v163, v163
	v_exp_f32_e32 v164, v164
	v_exp_f32_e32 v165, v165
	v_pk_add_f32 v[150:151], v[150:151], v[226:227]
	v_pk_add_f32 v[152:153], v[152:153], v[226:227]
	v_pk_add_f32 v[154:155], v[154:155], v[226:227]
	v_pk_add_f32 v[156:157], v[156:157], v[226:227]
	v_pk_add_f32 v[158:159], v[158:159], v[226:227]
	v_pk_add_f32 v[160:161], v[160:161], v[226:227]
	v_pk_add_f32 v[162:163], v[162:163], v[226:227]
	v_pk_add_f32 v[164:165], v[164:165], v[226:227]
	v_rcp_f32_e32 v150, v150
	v_rcp_f32_e32 v151, v151
	v_rcp_f32_e32 v152, v152
	v_rcp_f32_e32 v153, v153
	v_rcp_f32_e32 v154, v154
	v_rcp_f32_e32 v155, v155
	v_rcp_f32_e32 v156, v156
	v_rcp_f32_e32 v157, v157
	v_rcp_f32_e32 v158, v158
	v_rcp_f32_e32 v159, v159
	v_rcp_f32_e32 v160, v160
	v_rcp_f32_e32 v161, v161
	v_rcp_f32_e32 v162, v162
	v_rcp_f32_e32 v163, v163
	v_rcp_f32_e32 v164, v164
	v_rcp_f32_e32 v165, v165
	v_pk_mul_f32 v[166:167], v[110:111], v[224:225]
	v_pk_mul_f32 v[168:169], v[112:113], v[224:225]
	v_pk_mul_f32 v[170:171], v[106:107], v[224:225]
	v_pk_mul_f32 v[172:173], v[108:109], v[224:225]
	v_pk_mul_f32 v[174:175], v[102:103], v[224:225]
	v_pk_mul_f32 v[176:177], v[104:105], v[224:225]
	v_pk_mul_f32 v[178:179], v[98:99], v[224:225]
	v_pk_mul_f32 v[180:181], v[100:101], v[224:225]
	v_exp_f32_e32 v166, v166
	v_exp_f32_e32 v167, v167
	v_exp_f32_e32 v168, v168
	v_exp_f32_e32 v169, v169
	v_exp_f32_e32 v170, v170
	v_exp_f32_e32 v171, v171
	v_exp_f32_e32 v172, v172
	v_exp_f32_e32 v173, v173
	v_exp_f32_e32 v174, v174
	v_exp_f32_e32 v175, v175
	v_exp_f32_e32 v176, v176
	v_exp_f32_e32 v177, v177
	v_exp_f32_e32 v178, v178
	v_exp_f32_e32 v179, v179
	v_exp_f32_e32 v180, v180
	v_exp_f32_e32 v181, v181
	v_pk_add_f32 v[166:167], v[166:167], v[226:227]
	v_pk_add_f32 v[168:169], v[168:169], v[226:227]
	v_pk_add_f32 v[170:171], v[170:171], v[226:227]
	v_pk_add_f32 v[172:173], v[172:173], v[226:227]
	v_pk_add_f32 v[174:175], v[174:175], v[226:227]
	v_pk_add_f32 v[176:177], v[176:177], v[226:227]
	v_pk_add_f32 v[178:179], v[178:179], v[226:227]
	v_pk_add_f32 v[180:181], v[180:181], v[226:227]
	v_rcp_f32_e32 v166, v166
	v_rcp_f32_e32 v167, v167
	v_rcp_f32_e32 v168, v168
	v_rcp_f32_e32 v169, v169
	v_rcp_f32_e32 v170, v170
	v_rcp_f32_e32 v171, v171
	v_rcp_f32_e32 v172, v172
	v_rcp_f32_e32 v173, v173
	v_rcp_f32_e32 v174, v174
	v_rcp_f32_e32 v175, v175
	v_rcp_f32_e32 v176, v176
	v_rcp_f32_e32 v177, v177
	v_rcp_f32_e32 v178, v178
	v_rcp_f32_e32 v179, v179
	v_rcp_f32_e32 v180, v180
	v_rcp_f32_e32 v181, v181
	v_pk_mul_f32 v[182:183], v[94:95], v[224:225]
	v_pk_mul_f32 v[184:185], v[96:97], v[224:225]
	v_pk_mul_f32 v[186:187], v[90:91], v[224:225]
	v_pk_mul_f32 v[188:189], v[92:93], v[224:225]
	v_pk_mul_f32 v[190:191], v[86:87], v[224:225]
	v_pk_mul_f32 v[192:193], v[88:89], v[224:225]
	v_pk_mul_f32 v[194:195], v[82:83], v[224:225]
	v_pk_mul_f32 v[196:197], v[84:85], v[224:225]
	v_exp_f32_e32 v182, v182
	v_exp_f32_e32 v183, v183
	v_exp_f32_e32 v184, v184
	v_exp_f32_e32 v185, v185
	v_exp_f32_e32 v186, v186
	v_exp_f32_e32 v187, v187
	v_exp_f32_e32 v188, v188
	v_exp_f32_e32 v189, v189
	v_exp_f32_e32 v190, v190
	v_exp_f32_e32 v191, v191
	v_exp_f32_e32 v192, v192
	v_exp_f32_e32 v193, v193
	v_exp_f32_e32 v194, v194
	v_exp_f32_e32 v195, v195
	v_exp_f32_e32 v196, v196
	v_exp_f32_e32 v197, v197
	v_pk_add_f32 v[182:183], v[182:183], v[226:227]
	v_pk_add_f32 v[184:185], v[184:185], v[226:227]
	v_pk_add_f32 v[186:187], v[186:187], v[226:227]
	v_pk_add_f32 v[188:189], v[188:189], v[226:227]
	v_pk_add_f32 v[190:191], v[190:191], v[226:227]
	v_pk_add_f32 v[192:193], v[192:193], v[226:227]
	v_pk_add_f32 v[194:195], v[194:195], v[226:227]
	v_pk_add_f32 v[196:197], v[196:197], v[226:227]
	v_rcp_f32_e32 v182, v182
	v_rcp_f32_e32 v183, v183
	v_rcp_f32_e32 v184, v184
	v_rcp_f32_e32 v185, v185
	v_rcp_f32_e32 v186, v186
	v_rcp_f32_e32 v187, v187
	v_rcp_f32_e32 v188, v188
	v_rcp_f32_e32 v189, v189
	v_rcp_f32_e32 v190, v190
	v_rcp_f32_e32 v191, v191
	v_rcp_f32_e32 v192, v192
	v_rcp_f32_e32 v193, v193
	v_rcp_f32_e32 v194, v194
	v_rcp_f32_e32 v195, v195
	v_rcp_f32_e32 v196, v196
	v_rcp_f32_e32 v197, v197
	s_waitcnt vmcnt(1)
	s_barrier
	v_add_u32_e32 v253, 0x20000, v143
	s_add_i32 m0, s27, 0x4000
	s_nop 0
	global_load_lds_dwordx4 v253, s[6:7] nt
	ds_read_b64 v[140:141], v252 offset:0
	ds_read_b64 v[144:145], v252 offset:4096
	v_pk_mul_f32 v[230:231], v[78:79], v[224:225]
	v_pk_mul_f32 v[232:233], v[80:81], v[224:225]
	v_pk_mul_f32 v[234:235], v[74:75], v[224:225]
	v_pk_mul_f32 v[236:237], v[76:77], v[224:225]
	v_exp_f32_e32 v230, v230
	v_exp_f32_e32 v231, v231
	v_exp_f32_e32 v232, v232
	v_exp_f32_e32 v233, v233
	v_exp_f32_e32 v234, v234
	v_exp_f32_e32 v235, v235
	v_exp_f32_e32 v236, v236
	v_exp_f32_e32 v237, v237
	v_pk_add_f32 v[230:231], v[230:231], v[226:227]
	v_pk_add_f32 v[232:233], v[232:233], v[226:227]
	v_pk_add_f32 v[234:235], v[234:235], v[226:227]
	v_pk_add_f32 v[236:237], v[236:237], v[226:227]
	v_rcp_f32_e32 v230, v230
	v_rcp_f32_e32 v231, v231
	v_rcp_f32_e32 v232, v232
	v_rcp_f32_e32 v233, v233
	v_rcp_f32_e32 v234, v234
	v_rcp_f32_e32 v235, v235
	v_rcp_f32_e32 v236, v236
	v_rcp_f32_e32 v237, v237
	s_waitcnt lgkmcnt(0)
	v_lshlrev_b32_e32 v126, 16, v140
	v_and_b32_e32 v127, 0xffff0000, v140
	v_lshlrev_b32_e32 v128, 16, v141
	v_and_b32_e32 v129, 0xffff0000, v141
	v_lshlrev_b32_e32 v122, 16, v144
	v_and_b32_e32 v123, 0xffff0000, v144
	v_lshlrev_b32_e32 v124, 16, v145
	v_and_b32_e32 v125, 0xffff0000, v145
	v_pk_mul_f32 v[150:151], v[150:151], v[126:127]
	v_pk_mul_f32 v[152:153], v[152:153], v[128:129]
	v_pk_mul_f32 v[154:155], v[154:155], v[122:123]
	v_pk_mul_f32 v[156:157], v[156:157], v[124:125]
	v_pk_add_f32 v[246:247], v[150:151], v[228:229]
	v_pk_add_f32 v[248:249], v[152:153], v[228:229]
	v_pk_add_f32 v[246:247], v[246:247], v[154:155]
	v_pk_add_f32 v[248:249], v[248:249], v[156:157]
	s_waitcnt vmcnt(1)
	s_barrier
	v_add_u32_e32 v253, 0x21000, v143
	s_add_i32 m0, s27, 0x0
	s_nop 0
	global_load_lds_dwordx4 v253, s[6:7] nt
	ds_read_b64 v[140:141], v252 offset:8192
	ds_read_b64 v[144:145], v252 offset:12288
	v_pk_mul_f32 v[238:239], v[70:71], v[224:225]
	v_pk_mul_f32 v[240:241], v[72:73], v[224:225]
	v_pk_mul_f32 v[242:243], v[66:67], v[224:225]
	v_pk_mul_f32 v[244:245], v[68:69], v[224:225]
	v_exp_f32_e32 v238, v238
	v_exp_f32_e32 v239, v239
	v_exp_f32_e32 v240, v240
	v_exp_f32_e32 v241, v241
	v_exp_f32_e32 v242, v242
	v_exp_f32_e32 v243, v243
	v_exp_f32_e32 v244, v244
	v_exp_f32_e32 v245, v245
	v_pk_add_f32 v[238:239], v[238:239], v[226:227]
	v_pk_add_f32 v[240:241], v[240:241], v[226:227]
	v_pk_add_f32 v[242:243], v[242:243], v[226:227]
	v_pk_add_f32 v[244:245], v[244:245], v[226:227]
	v_rcp_f32_e32 v238, v238
	v_rcp_f32_e32 v239, v239
	v_rcp_f32_e32 v240, v240
	v_rcp_f32_e32 v241, v241
	v_rcp_f32_e32 v242, v242
	v_rcp_f32_e32 v243, v243
	v_rcp_f32_e32 v244, v244
	v_rcp_f32_e32 v245, v245
	s_waitcnt lgkmcnt(0)
	v_lshlrev_b32_e32 v118, 16, v140
	v_and_b32_e32 v119, 0xffff0000, v140
	v_lshlrev_b32_e32 v120, 16, v141
	v_and_b32_e32 v121, 0xffff0000, v141
	v_lshlrev_b32_e32 v114, 16, v144
	v_and_b32_e32 v115, 0xffff0000, v144
	v_lshlrev_b32_e32 v116, 16, v145
	v_and_b32_e32 v117, 0xffff0000, v145
	v_pk_mul_f32 v[158:159], v[158:159], v[118:119]
	v_pk_mul_f32 v[160:161], v[160:161], v[120:121]
	v_pk_mul_f32 v[162:163], v[162:163], v[114:115]
	v_pk_mul_f32 v[164:165], v[164:165], v[116:117]
	v_pk_add_f32 v[246:247], v[246:247], v[158:159]
	v_pk_add_f32 v[248:249], v[248:249], v[160:161]
	v_pk_add_f32 v[246:247], v[246:247], v[162:163]
	v_pk_add_f32 v[248:249], v[248:249], v[164:165]
	v_add_u32_e32 v254, 0, v250
	v_cvt_pk_bf16_f32 v246, v246, v247
	v_cvt_pk_bf16_f32 v247, v248, v249
	v_lshl_add_u32 v254, v254, 11, v251
	s_nop 0
	global_store_dwordx2 v254, v[246:247], s[8:9]
	s_waitcnt vmcnt(2)
	s_barrier
	v_add_u32_e32 v253, 0x40000, v143
	s_add_i32 m0, s27, 0x2000
	s_nop 0
	global_load_lds_dwordx4 v253, s[6:7] nt
	ds_read_b64 v[140:141], v252 offset:16384
	ds_read_b64 v[144:145], v252 offset:20480
	v_pk_mul_f32 v[150:151], v[62:63], v[224:225]
	v_pk_mul_f32 v[152:153], v[64:65], v[224:225]
	v_pk_mul_f32 v[154:155], v[58:59], v[224:225]
	v_pk_mul_f32 v[156:157], v[60:61], v[224:225]
	v_exp_f32_e32 v150, v150
	v_exp_f32_e32 v151, v151
	v_exp_f32_e32 v152, v152
	v_exp_f32_e32 v153, v153
	v_exp_f32_e32 v154, v154
	v_exp_f32_e32 v155, v155
	v_exp_f32_e32 v156, v156
	v_exp_f32_e32 v157, v157
	v_pk_add_f32 v[150:151], v[150:151], v[226:227]
	v_pk_add_f32 v[152:153], v[152:153], v[226:227]
	v_pk_add_f32 v[154:155], v[154:155], v[226:227]
	v_pk_add_f32 v[156:157], v[156:157], v[226:227]
	v_rcp_f32_e32 v150, v150
	v_rcp_f32_e32 v151, v151
	v_rcp_f32_e32 v152, v152
	v_rcp_f32_e32 v153, v153
	v_rcp_f32_e32 v154, v154
	v_rcp_f32_e32 v155, v155
	v_rcp_f32_e32 v156, v156
	v_rcp_f32_e32 v157, v157
	s_waitcnt lgkmcnt(0)
	v_lshlrev_b32_e32 v110, 16, v140
	v_and_b32_e32 v111, 0xffff0000, v140
	v_lshlrev_b32_e32 v112, 16, v141
	v_and_b32_e32 v113, 0xffff0000, v141
	v_lshlrev_b32_e32 v106, 16, v144
	v_and_b32_e32 v107, 0xffff0000, v144
	v_lshlrev_b32_e32 v108, 16, v145
	v_and_b32_e32 v109, 0xffff0000, v145
	v_pk_mul_f32 v[166:167], v[166:167], v[110:111]
	v_pk_mul_f32 v[168:169], v[168:169], v[112:113]
	v_pk_mul_f32 v[170:171], v[170:171], v[106:107]
	v_pk_mul_f32 v[172:173], v[172:173], v[108:109]
	v_pk_add_f32 v[246:247], v[166:167], v[228:229]
	v_pk_add_f32 v[248:249], v[168:169], v[228:229]
	v_pk_add_f32 v[246:247], v[246:247], v[170:171]
	v_pk_add_f32 v[248:249], v[248:249], v[172:173]
	s_waitcnt vmcnt(2)
	s_barrier
	v_add_u32_e32 v253, 0x41000, v143
	s_add_i32 m0, s27, 0x4000
	s_nop 0
	global_load_lds_dwordx4 v253, s[6:7] nt
	ds_read_b64 v[140:141], v252 offset:0
	ds_read_b64 v[144:145], v252 offset:4096
	v_pk_mul_f32 v[158:159], v[54:55], v[224:225]
	v_pk_mul_f32 v[160:161], v[56:57], v[224:225]
	v_pk_mul_f32 v[162:163], v[50:51], v[224:225]
	v_pk_mul_f32 v[164:165], v[52:53], v[224:225]
	v_exp_f32_e32 v158, v158
	v_exp_f32_e32 v159, v159
	v_exp_f32_e32 v160, v160
	v_exp_f32_e32 v161, v161
	v_exp_f32_e32 v162, v162
	v_exp_f32_e32 v163, v163
	v_exp_f32_e32 v164, v164
	v_exp_f32_e32 v165, v165
	v_pk_add_f32 v[158:159], v[158:159], v[226:227]
	v_pk_add_f32 v[160:161], v[160:161], v[226:227]
	v_pk_add_f32 v[162:163], v[162:163], v[226:227]
	v_pk_add_f32 v[164:165], v[164:165], v[226:227]
	v_rcp_f32_e32 v158, v158
	v_rcp_f32_e32 v159, v159
	v_rcp_f32_e32 v160, v160
	v_rcp_f32_e32 v161, v161
	v_rcp_f32_e32 v162, v162
	v_rcp_f32_e32 v163, v163
	v_rcp_f32_e32 v164, v164
	v_rcp_f32_e32 v165, v165
	s_waitcnt lgkmcnt(0)
	v_lshlrev_b32_e32 v102, 16, v140
	v_and_b32_e32 v103, 0xffff0000, v140
	v_lshlrev_b32_e32 v104, 16, v141
	v_and_b32_e32 v105, 0xffff0000, v141
	v_lshlrev_b32_e32 v98, 16, v144
	v_and_b32_e32 v99, 0xffff0000, v144
	v_lshlrev_b32_e32 v100, 16, v145
	v_and_b32_e32 v101, 0xffff0000, v145
	v_pk_mul_f32 v[174:175], v[174:175], v[102:103]
	v_pk_mul_f32 v[176:177], v[176:177], v[104:105]
	v_pk_mul_f32 v[178:179], v[178:179], v[98:99]
	v_pk_mul_f32 v[180:181], v[180:181], v[100:101]
	v_pk_add_f32 v[246:247], v[246:247], v[174:175]
	v_pk_add_f32 v[248:249], v[248:249], v[176:177]
	v_pk_add_f32 v[246:247], v[246:247], v[178:179]
	v_pk_add_f32 v[248:249], v[248:249], v[180:181]
	v_add_u32_e32 v254, 16, v250
	v_cvt_pk_bf16_f32 v246, v246, v247
	v_cvt_pk_bf16_f32 v247, v248, v249
	v_lshl_add_u32 v254, v254, 11, v251
	s_nop 0
	global_store_dwordx2 v254, v[246:247], s[8:9]
	s_waitcnt vmcnt(2)
	s_barrier
	v_add_u32_e32 v253, 0x60000, v143
	s_add_i32 m0, s27, 0x0
	s_nop 0
	global_load_lds_dwordx4 v253, s[6:7] nt
	ds_read_b64 v[140:141], v252 offset:8192
	ds_read_b64 v[144:145], v252 offset:12288
	v_pk_mul_f32 v[166:167], v[46:47], v[224:225]
	v_pk_mul_f32 v[168:169], v[48:49], v[224:225]
	v_pk_mul_f32 v[170:171], v[42:43], v[224:225]
	v_pk_mul_f32 v[172:173], v[44:45], v[224:225]
	v_exp_f32_e32 v166, v166
	v_exp_f32_e32 v167, v167
	v_exp_f32_e32 v168, v168
	v_exp_f32_e32 v169, v169
	v_exp_f32_e32 v170, v170
	v_exp_f32_e32 v171, v171
	v_exp_f32_e32 v172, v172
	v_exp_f32_e32 v173, v173
	v_pk_add_f32 v[166:167], v[166:167], v[226:227]
	v_pk_add_f32 v[168:169], v[168:169], v[226:227]
	v_pk_add_f32 v[170:171], v[170:171], v[226:227]
	v_pk_add_f32 v[172:173], v[172:173], v[226:227]
	v_rcp_f32_e32 v166, v166
	v_rcp_f32_e32 v167, v167
	v_rcp_f32_e32 v168, v168
	v_rcp_f32_e32 v169, v169
	v_rcp_f32_e32 v170, v170
	v_rcp_f32_e32 v171, v171
	v_rcp_f32_e32 v172, v172
	v_rcp_f32_e32 v173, v173
	s_waitcnt lgkmcnt(0)
	v_lshlrev_b32_e32 v94, 16, v140
	v_and_b32_e32 v95, 0xffff0000, v140
	v_lshlrev_b32_e32 v96, 16, v141
	v_and_b32_e32 v97, 0xffff0000, v141
	v_lshlrev_b32_e32 v90, 16, v144
	v_and_b32_e32 v91, 0xffff0000, v144
	v_lshlrev_b32_e32 v92, 16, v145
	v_and_b32_e32 v93, 0xffff0000, v145
	v_pk_mul_f32 v[182:183], v[182:183], v[94:95]
	v_pk_mul_f32 v[184:185], v[184:185], v[96:97]
	v_pk_mul_f32 v[186:187], v[186:187], v[90:91]
	v_pk_mul_f32 v[188:189], v[188:189], v[92:93]
	v_pk_add_f32 v[246:247], v[182:183], v[228:229]
	v_pk_add_f32 v[248:249], v[184:185], v[228:229]
	v_pk_add_f32 v[246:247], v[246:247], v[186:187]
	v_pk_add_f32 v[248:249], v[248:249], v[188:189]
	s_waitcnt vmcnt(2)
	s_barrier
	v_add_u32_e32 v253, 0x61000, v143
	s_add_i32 m0, s27, 0x2000
	s_nop 0
	global_load_lds_dwordx4 v253, s[6:7] nt
	ds_read_b64 v[140:141], v252 offset:16384
	ds_read_b64 v[144:145], v252 offset:20480
	v_pk_mul_f32 v[174:175], v[38:39], v[224:225]
	v_pk_mul_f32 v[176:177], v[40:41], v[224:225]
	v_pk_mul_f32 v[178:179], v[34:35], v[224:225]
	v_pk_mul_f32 v[180:181], v[36:37], v[224:225]
	v_exp_f32_e32 v174, v174
	v_exp_f32_e32 v175, v175
	v_exp_f32_e32 v176, v176
	v_exp_f32_e32 v177, v177
	v_exp_f32_e32 v178, v178
	v_exp_f32_e32 v179, v179
	v_exp_f32_e32 v180, v180
	v_exp_f32_e32 v181, v181
	v_pk_add_f32 v[174:175], v[174:175], v[226:227]
	v_pk_add_f32 v[176:177], v[176:177], v[226:227]
	v_pk_add_f32 v[178:179], v[178:179], v[226:227]
	v_pk_add_f32 v[180:181], v[180:181], v[226:227]
	v_rcp_f32_e32 v174, v174
	v_rcp_f32_e32 v175, v175
	v_rcp_f32_e32 v176, v176
	v_rcp_f32_e32 v177, v177
	v_rcp_f32_e32 v178, v178
	v_rcp_f32_e32 v179, v179
	v_rcp_f32_e32 v180, v180
	v_rcp_f32_e32 v181, v181
	s_waitcnt lgkmcnt(0)
	v_lshlrev_b32_e32 v86, 16, v140
	v_and_b32_e32 v87, 0xffff0000, v140
	v_lshlrev_b32_e32 v88, 16, v141
	v_and_b32_e32 v89, 0xffff0000, v141
	v_lshlrev_b32_e32 v82, 16, v144
	v_and_b32_e32 v83, 0xffff0000, v144
	v_lshlrev_b32_e32 v84, 16, v145
	v_and_b32_e32 v85, 0xffff0000, v145
	v_pk_mul_f32 v[190:191], v[190:191], v[86:87]
	v_pk_mul_f32 v[192:193], v[192:193], v[88:89]
	v_pk_mul_f32 v[194:195], v[194:195], v[82:83]
	v_pk_mul_f32 v[196:197], v[196:197], v[84:85]
	v_pk_add_f32 v[246:247], v[246:247], v[190:191]
	v_pk_add_f32 v[248:249], v[248:249], v[192:193]
	v_pk_add_f32 v[246:247], v[246:247], v[194:195]
	v_pk_add_f32 v[248:249], v[248:249], v[196:197]
	v_add_u32_e32 v254, 32, v250
	v_cvt_pk_bf16_f32 v246, v246, v247
	v_cvt_pk_bf16_f32 v247, v248, v249
	v_lshl_add_u32 v254, v254, 11, v251
	s_nop 0
	global_store_dwordx2 v254, v[246:247], s[8:9]
	s_waitcnt vmcnt(2)
	s_barrier
	v_add_u32_e32 v253, 0x100000, v143
	s_add_i32 m0, s27, 0x4000
	s_nop 0
	global_load_lds_dwordx4 v253, s[6:7] nt
	ds_read_b64 v[140:141], v252 offset:0
	ds_read_b64 v[144:145], v252 offset:4096
	v_pk_mul_f32 v[182:183], v[30:31], v[224:225]
	v_pk_mul_f32 v[184:185], v[32:33], v[224:225]
	v_pk_mul_f32 v[186:187], v[26:27], v[224:225]
	v_pk_mul_f32 v[188:189], v[28:29], v[224:225]
	v_exp_f32_e32 v182, v182
	v_exp_f32_e32 v183, v183
	v_exp_f32_e32 v184, v184
	v_exp_f32_e32 v185, v185
	v_exp_f32_e32 v186, v186
	v_exp_f32_e32 v187, v187
	v_exp_f32_e32 v188, v188
	v_exp_f32_e32 v189, v189
	v_pk_add_f32 v[182:183], v[182:183], v[226:227]
	v_pk_add_f32 v[184:185], v[184:185], v[226:227]
	v_pk_add_f32 v[186:187], v[186:187], v[226:227]
	v_pk_add_f32 v[188:189], v[188:189], v[226:227]
	v_rcp_f32_e32 v182, v182
	v_rcp_f32_e32 v183, v183
	v_rcp_f32_e32 v184, v184
	v_rcp_f32_e32 v185, v185
	v_rcp_f32_e32 v186, v186
	v_rcp_f32_e32 v187, v187
	v_rcp_f32_e32 v188, v188
	v_rcp_f32_e32 v189, v189
	s_waitcnt lgkmcnt(0)
	v_lshlrev_b32_e32 v78, 16, v140
	v_and_b32_e32 v79, 0xffff0000, v140
	v_lshlrev_b32_e32 v80, 16, v141
	v_and_b32_e32 v81, 0xffff0000, v141
	v_lshlrev_b32_e32 v74, 16, v144
	v_and_b32_e32 v75, 0xffff0000, v144
	v_lshlrev_b32_e32 v76, 16, v145
	v_and_b32_e32 v77, 0xffff0000, v145
	v_pk_mul_f32 v[230:231], v[230:231], v[78:79]
	v_pk_mul_f32 v[232:233], v[232:233], v[80:81]
	v_pk_mul_f32 v[234:235], v[234:235], v[74:75]
	v_pk_mul_f32 v[236:237], v[236:237], v[76:77]
	v_pk_add_f32 v[246:247], v[230:231], v[228:229]
	v_pk_add_f32 v[248:249], v[232:233], v[228:229]
	v_pk_add_f32 v[246:247], v[246:247], v[234:235]
	v_pk_add_f32 v[248:249], v[248:249], v[236:237]
	s_waitcnt vmcnt(2)
	s_barrier
	v_add_u32_e32 v253, 0x101000, v143
	s_add_i32 m0, s27, 0x0
	s_nop 0
	global_load_lds_dwordx4 v253, s[6:7] nt
	ds_read_b64 v[140:141], v252 offset:8192
	ds_read_b64 v[144:145], v252 offset:12288
	v_pk_mul_f32 v[190:191], v[22:23], v[224:225]
	v_pk_mul_f32 v[192:193], v[24:25], v[224:225]
	v_pk_mul_f32 v[194:195], v[18:19], v[224:225]
	v_pk_mul_f32 v[196:197], v[20:21], v[224:225]
	v_exp_f32_e32 v190, v190
	v_exp_f32_e32 v191, v191
	v_exp_f32_e32 v192, v192
	v_exp_f32_e32 v193, v193
	v_exp_f32_e32 v194, v194
	v_exp_f32_e32 v195, v195
	v_exp_f32_e32 v196, v196
	v_exp_f32_e32 v197, v197
	v_pk_add_f32 v[190:191], v[190:191], v[226:227]
	v_pk_add_f32 v[192:193], v[192:193], v[226:227]
	v_pk_add_f32 v[194:195], v[194:195], v[226:227]
	v_pk_add_f32 v[196:197], v[196:197], v[226:227]
	v_rcp_f32_e32 v190, v190
	v_rcp_f32_e32 v191, v191
	v_rcp_f32_e32 v192, v192
	v_rcp_f32_e32 v193, v193
	v_rcp_f32_e32 v194, v194
	v_rcp_f32_e32 v195, v195
	v_rcp_f32_e32 v196, v196
	v_rcp_f32_e32 v197, v197
	s_waitcnt lgkmcnt(0)
	v_lshlrev_b32_e32 v70, 16, v140
	v_and_b32_e32 v71, 0xffff0000, v140
	v_lshlrev_b32_e32 v72, 16, v141
	v_and_b32_e32 v73, 0xffff0000, v141
	v_lshlrev_b32_e32 v66, 16, v144
	v_and_b32_e32 v67, 0xffff0000, v144
	v_lshlrev_b32_e32 v68, 16, v145
	v_and_b32_e32 v69, 0xffff0000, v145
	v_pk_mul_f32 v[238:239], v[238:239], v[70:71]
	v_pk_mul_f32 v[240:241], v[240:241], v[72:73]
	v_pk_mul_f32 v[242:243], v[242:243], v[66:67]
	v_pk_mul_f32 v[244:245], v[244:245], v[68:69]
	v_pk_add_f32 v[246:247], v[246:247], v[238:239]
	v_pk_add_f32 v[248:249], v[248:249], v[240:241]
	v_pk_add_f32 v[246:247], v[246:247], v[242:243]
	v_pk_add_f32 v[248:249], v[248:249], v[244:245]
	v_add_u32_e32 v254, 48, v250
	v_cvt_pk_bf16_f32 v246, v246, v247
	v_cvt_pk_bf16_f32 v247, v248, v249
	v_lshl_add_u32 v254, v254, 11, v251
	s_nop 0
	global_store_dwordx2 v254, v[246:247], s[8:9]
	s_waitcnt vmcnt(2)
	s_barrier
	v_add_u32_e32 v253, 0x120000, v143
	s_add_i32 m0, s27, 0x2000
	s_nop 0
	global_load_lds_dwordx4 v253, s[6:7] nt
	ds_read_b64 v[140:141], v252 offset:16384
	ds_read_b64 v[144:145], v252 offset:20480
	v_pk_mul_f32 v[230:231], v[14:15], v[224:225]
	v_pk_mul_f32 v[232:233], v[16:17], v[224:225]
	v_pk_mul_f32 v[234:235], v[10:11], v[224:225]
	v_pk_mul_f32 v[236:237], v[12:13], v[224:225]
	v_exp_f32_e32 v230, v230
	v_exp_f32_e32 v231, v231
	v_exp_f32_e32 v232, v232
	v_exp_f32_e32 v233, v233
	v_exp_f32_e32 v234, v234
	v_exp_f32_e32 v235, v235
	v_exp_f32_e32 v236, v236
	v_exp_f32_e32 v237, v237
	v_pk_add_f32 v[230:231], v[230:231], v[226:227]
	v_pk_add_f32 v[232:233], v[232:233], v[226:227]
	v_pk_add_f32 v[234:235], v[234:235], v[226:227]
	v_pk_add_f32 v[236:237], v[236:237], v[226:227]
	v_rcp_f32_e32 v230, v230
	v_rcp_f32_e32 v231, v231
	v_rcp_f32_e32 v232, v232
	v_rcp_f32_e32 v233, v233
	v_rcp_f32_e32 v234, v234
	v_rcp_f32_e32 v235, v235
	v_rcp_f32_e32 v236, v236
	v_rcp_f32_e32 v237, v237
	s_waitcnt lgkmcnt(0)
	v_lshlrev_b32_e32 v62, 16, v140
	v_and_b32_e32 v63, 0xffff0000, v140
	v_lshlrev_b32_e32 v64, 16, v141
	v_and_b32_e32 v65, 0xffff0000, v141
	v_lshlrev_b32_e32 v58, 16, v144
	v_and_b32_e32 v59, 0xffff0000, v144
	v_lshlrev_b32_e32 v60, 16, v145
	v_and_b32_e32 v61, 0xffff0000, v145
	v_pk_mul_f32 v[150:151], v[150:151], v[62:63]
	v_pk_mul_f32 v[152:153], v[152:153], v[64:65]
	v_pk_mul_f32 v[154:155], v[154:155], v[58:59]
	v_pk_mul_f32 v[156:157], v[156:157], v[60:61]
	v_pk_add_f32 v[246:247], v[150:151], v[228:229]
	v_pk_add_f32 v[248:249], v[152:153], v[228:229]
	v_pk_add_f32 v[246:247], v[246:247], v[154:155]
	v_pk_add_f32 v[248:249], v[248:249], v[156:157]
	s_waitcnt vmcnt(2)
	s_barrier
	v_add_u32_e32 v253, 0x121000, v143
	s_add_i32 m0, s27, 0x4000
	s_nop 0
	global_load_lds_dwordx4 v253, s[6:7] nt
	ds_read_b64 v[140:141], v252 offset:0
	ds_read_b64 v[144:145], v252 offset:4096
	v_pk_mul_f32 v[238:239], v[6:7], v[224:225]
	v_pk_mul_f32 v[240:241], v[8:9], v[224:225]
	v_pk_mul_f32 v[242:243], v[2:3], v[224:225]
	v_pk_mul_f32 v[244:245], v[4:5], v[224:225]
	v_exp_f32_e32 v238, v238
	v_exp_f32_e32 v239, v239
	v_exp_f32_e32 v240, v240
	v_exp_f32_e32 v241, v241
	v_exp_f32_e32 v242, v242
	v_exp_f32_e32 v243, v243
	v_exp_f32_e32 v244, v244
	v_exp_f32_e32 v245, v245
	v_pk_add_f32 v[238:239], v[238:239], v[226:227]
	v_pk_add_f32 v[240:241], v[240:241], v[226:227]
	v_pk_add_f32 v[242:243], v[242:243], v[226:227]
	v_pk_add_f32 v[244:245], v[244:245], v[226:227]
	v_rcp_f32_e32 v238, v238
	v_rcp_f32_e32 v239, v239
	v_rcp_f32_e32 v240, v240
	v_rcp_f32_e32 v241, v241
	v_rcp_f32_e32 v242, v242
	v_rcp_f32_e32 v243, v243
	v_rcp_f32_e32 v244, v244
	v_rcp_f32_e32 v245, v245
	s_waitcnt lgkmcnt(0)
	v_lshlrev_b32_e32 v54, 16, v140
	v_and_b32_e32 v55, 0xffff0000, v140
	v_lshlrev_b32_e32 v56, 16, v141
	v_and_b32_e32 v57, 0xffff0000, v141
	v_lshlrev_b32_e32 v50, 16, v144
	v_and_b32_e32 v51, 0xffff0000, v144
	v_lshlrev_b32_e32 v52, 16, v145
	v_and_b32_e32 v53, 0xffff0000, v145
	v_pk_mul_f32 v[158:159], v[158:159], v[54:55]
	v_pk_mul_f32 v[160:161], v[160:161], v[56:57]
	v_pk_mul_f32 v[162:163], v[162:163], v[50:51]
	v_pk_mul_f32 v[164:165], v[164:165], v[52:53]
	v_pk_add_f32 v[246:247], v[246:247], v[158:159]
	v_pk_add_f32 v[248:249], v[248:249], v[160:161]
	v_pk_add_f32 v[246:247], v[246:247], v[162:163]
	v_pk_add_f32 v[248:249], v[248:249], v[164:165]
	v_add_u32_e32 v254, 128, v250
	v_cvt_pk_bf16_f32 v246, v246, v247
	v_cvt_pk_bf16_f32 v247, v248, v249
	v_lshl_add_u32 v254, v254, 11, v251
	s_nop 0
	global_store_dwordx2 v254, v[246:247], s[8:9]
	s_waitcnt vmcnt(2)
	s_barrier
	v_add_u32_e32 v253, 0x140000, v143
	s_add_i32 m0, s27, 0x0
	s_nop 0
	global_load_lds_dwordx4 v253, s[6:7] nt
	ds_read_b64 v[140:141], v252 offset:8192
	ds_read_b64 v[144:145], v252 offset:12288
	s_waitcnt lgkmcnt(0)
	v_lshlrev_b32_e32 v46, 16, v140
	v_and_b32_e32 v47, 0xffff0000, v140
	v_lshlrev_b32_e32 v48, 16, v141
	v_and_b32_e32 v49, 0xffff0000, v141
	v_lshlrev_b32_e32 v42, 16, v144
	v_and_b32_e32 v43, 0xffff0000, v144
	v_lshlrev_b32_e32 v44, 16, v145
	v_and_b32_e32 v45, 0xffff0000, v145
	v_pk_mul_f32 v[166:167], v[166:167], v[46:47]
	v_pk_mul_f32 v[168:169], v[168:169], v[48:49]
	v_pk_mul_f32 v[170:171], v[170:171], v[42:43]
	v_pk_mul_f32 v[172:173], v[172:173], v[44:45]
	v_pk_add_f32 v[246:247], v[166:167], v[228:229]
	v_pk_add_f32 v[248:249], v[168:169], v[228:229]
	v_pk_add_f32 v[246:247], v[246:247], v[170:171]
	v_pk_add_f32 v[248:249], v[248:249], v[172:173]
	s_waitcnt vmcnt(2)
	s_barrier
	v_add_u32_e32 v253, 0x141000, v143
	s_add_i32 m0, s27, 0x2000
	s_nop 0
	global_load_lds_dwordx4 v253, s[6:7] nt
	ds_read_b64 v[140:141], v252 offset:16384
	ds_read_b64 v[144:145], v252 offset:20480
	s_waitcnt lgkmcnt(0)
	v_lshlrev_b32_e32 v38, 16, v140
	v_and_b32_e32 v39, 0xffff0000, v140
	v_lshlrev_b32_e32 v40, 16, v141
	v_and_b32_e32 v41, 0xffff0000, v141
	v_lshlrev_b32_e32 v34, 16, v144
	v_and_b32_e32 v35, 0xffff0000, v144
	v_lshlrev_b32_e32 v36, 16, v145
	v_and_b32_e32 v37, 0xffff0000, v145
	v_pk_mul_f32 v[174:175], v[174:175], v[38:39]
	v_pk_mul_f32 v[176:177], v[176:177], v[40:41]
	v_pk_mul_f32 v[178:179], v[178:179], v[34:35]
	v_pk_mul_f32 v[180:181], v[180:181], v[36:37]
	v_pk_add_f32 v[246:247], v[246:247], v[174:175]
	v_pk_add_f32 v[248:249], v[248:249], v[176:177]
	v_pk_add_f32 v[246:247], v[246:247], v[178:179]
	v_pk_add_f32 v[248:249], v[248:249], v[180:181]
	v_add_u32_e32 v254, 144, v250
	v_cvt_pk_bf16_f32 v246, v246, v247
	v_cvt_pk_bf16_f32 v247, v248, v249
	v_lshl_add_u32 v254, v254, 11, v251
	s_nop 0
	global_store_dwordx2 v254, v[246:247], s[8:9]
	s_waitcnt vmcnt(2)
	s_barrier
	v_add_u32_e32 v253, 0x160000, v143
	s_add_i32 m0, s27, 0x4000
	s_nop 0
	global_load_lds_dwordx4 v253, s[6:7] nt
	ds_read_b64 v[140:141], v252 offset:0
	ds_read_b64 v[144:145], v252 offset:4096
	s_waitcnt lgkmcnt(0)
	v_lshlrev_b32_e32 v30, 16, v140
	v_and_b32_e32 v31, 0xffff0000, v140
	v_lshlrev_b32_e32 v32, 16, v141
	v_and_b32_e32 v33, 0xffff0000, v141
	v_lshlrev_b32_e32 v26, 16, v144
	v_and_b32_e32 v27, 0xffff0000, v144
	v_lshlrev_b32_e32 v28, 16, v145
	v_and_b32_e32 v29, 0xffff0000, v145
	v_pk_mul_f32 v[182:183], v[182:183], v[30:31]
	v_pk_mul_f32 v[184:185], v[184:185], v[32:33]
	v_pk_mul_f32 v[186:187], v[186:187], v[26:27]
	v_pk_mul_f32 v[188:189], v[188:189], v[28:29]
	v_pk_add_f32 v[246:247], v[182:183], v[228:229]
	v_pk_add_f32 v[248:249], v[184:185], v[228:229]
	v_pk_add_f32 v[246:247], v[246:247], v[186:187]
	v_pk_add_f32 v[248:249], v[248:249], v[188:189]
	s_waitcnt vmcnt(2)
	s_barrier
	v_add_u32_e32 v253, 0x161000, v143
	s_add_i32 m0, s27, 0x0
	s_nop 0
	global_load_lds_dwordx4 v253, s[6:7] nt
	ds_read_b64 v[140:141], v252 offset:8192
	ds_read_b64 v[144:145], v252 offset:12288
	s_waitcnt lgkmcnt(0)
	v_lshlrev_b32_e32 v22, 16, v140
	v_and_b32_e32 v23, 0xffff0000, v140
	v_lshlrev_b32_e32 v24, 16, v141
	v_and_b32_e32 v25, 0xffff0000, v141
	v_lshlrev_b32_e32 v18, 16, v144
	v_and_b32_e32 v19, 0xffff0000, v144
	v_lshlrev_b32_e32 v20, 16, v145
	v_and_b32_e32 v21, 0xffff0000, v145
	v_pk_mul_f32 v[190:191], v[190:191], v[22:23]
	v_pk_mul_f32 v[192:193], v[192:193], v[24:25]
	v_pk_mul_f32 v[194:195], v[194:195], v[18:19]
	v_pk_mul_f32 v[196:197], v[196:197], v[20:21]
	v_pk_add_f32 v[246:247], v[246:247], v[190:191]
	v_pk_add_f32 v[248:249], v[248:249], v[192:193]
	v_pk_add_f32 v[246:247], v[246:247], v[194:195]
	v_pk_add_f32 v[248:249], v[248:249], v[196:197]
	v_add_u32_e32 v254, 160, v250
	v_cvt_pk_bf16_f32 v246, v246, v247
	v_cvt_pk_bf16_f32 v247, v248, v249
	v_lshl_add_u32 v254, v254, 11, v251
	s_nop 0
	global_store_dwordx2 v254, v[246:247], s[8:9]
	s_waitcnt vmcnt(2)
	s_barrier
	ds_read_b64 v[140:141], v252 offset:16384
	ds_read_b64 v[144:145], v252 offset:20480
	s_waitcnt lgkmcnt(0)
	v_lshlrev_b32_e32 v14, 16, v140
	v_and_b32_e32 v15, 0xffff0000, v140
	v_lshlrev_b32_e32 v16, 16, v141
	v_and_b32_e32 v17, 0xffff0000, v141
	v_lshlrev_b32_e32 v10, 16, v144
	v_and_b32_e32 v11, 0xffff0000, v144
	v_lshlrev_b32_e32 v12, 16, v145
	v_and_b32_e32 v13, 0xffff0000, v145
	v_pk_mul_f32 v[230:231], v[230:231], v[14:15]
	v_pk_mul_f32 v[232:233], v[232:233], v[16:17]
	v_pk_mul_f32 v[234:235], v[234:235], v[10:11]
	v_pk_mul_f32 v[236:237], v[236:237], v[12:13]
	v_pk_add_f32 v[246:247], v[230:231], v[228:229]
	v_pk_add_f32 v[248:249], v[232:233], v[228:229]
	v_pk_add_f32 v[246:247], v[246:247], v[234:235]
	v_pk_add_f32 v[248:249], v[248:249], v[236:237]
	s_waitcnt vmcnt(1)
	s_barrier
	ds_read_b64 v[140:141], v252 offset:0
	ds_read_b64 v[144:145], v252 offset:4096
	s_waitcnt lgkmcnt(0)
	v_lshlrev_b32_e32 v6, 16, v140
	v_and_b32_e32 v7, 0xffff0000, v140
	v_lshlrev_b32_e32 v8, 16, v141
	v_and_b32_e32 v9, 0xffff0000, v141
	v_lshlrev_b32_e32 v2, 16, v144
	v_and_b32_e32 v3, 0xffff0000, v144
	v_lshlrev_b32_e32 v4, 16, v145
	v_and_b32_e32 v5, 0xffff0000, v145
	v_pk_mul_f32 v[238:239], v[238:239], v[6:7]
	v_pk_mul_f32 v[240:241], v[240:241], v[8:9]
	v_pk_mul_f32 v[242:243], v[242:243], v[2:3]
	v_pk_mul_f32 v[244:245], v[244:245], v[4:5]
	v_pk_add_f32 v[246:247], v[246:247], v[238:239]
	v_pk_add_f32 v[248:249], v[248:249], v[240:241]
	v_pk_add_f32 v[246:247], v[246:247], v[242:243]
	v_pk_add_f32 v[248:249], v[248:249], v[244:245]
	v_add_u32_e32 v254, 176, v250
	v_cvt_pk_bf16_f32 v246, v246, v247
	v_cvt_pk_bf16_f32 v247, v248, v249
	v_lshl_add_u32 v254, v254, 11, v251
	s_nop 0
	global_store_dwordx2 v254, v[246:247], s[8:9]
	s_mov_b64 s[26:27], -1
	s_andn2_b64 vcc, exec, s[4:5]
	s_cbranch_vccnz .LBB0_1599
	s_andn2_b64 vcc, exec, s[0:1]
	s_cbranch_vccnz .LBB0_1598
	s_barrier
	s_branch .LBB0_1598
